# phase_mod (adaLN vectors): all 32 w_ada loads of each 32-k step issued up front with counted vmcnt (was four drained 8-load batches)
# speedup vs baseline: 1.0075x; 1.0060x over previous
.LBB0_17:
	v_mad_i64_i32 v[232:233], s[2:3], v94, s23, v[56:57]
	global_load_dword v104, v[232:233], off
	v_or_b32_e32 v232, 1, v94
	v_mad_i64_i32 v[232:233], s[2:3], v232, s23, v[56:57]
	global_load_dword v106, v[232:233], off
	v_or_b32_e32 v232, 2, v94
	v_mad_i64_i32 v[232:233], s[2:3], v232, s23, v[56:57]
	global_load_dword v108, v[232:233], off
	v_or_b32_e32 v232, 3, v94
	v_mad_i64_i32 v[232:233], s[2:3], v232, s23, v[56:57]
	global_load_dword v110, v[232:233], off
	v_or_b32_e32 v232, 4, v94
	v_mad_i64_i32 v[232:233], s[2:3], v232, s23, v[56:57]
	global_load_dword v112, v[232:233], off
	v_or_b32_e32 v232, 5, v94
	v_mad_i64_i32 v[232:233], s[2:3], v232, s23, v[56:57]
	global_load_dword v114, v[232:233], off
	v_or_b32_e32 v232, 6, v94
	v_mad_i64_i32 v[232:233], s[2:3], v232, s23, v[56:57]
	global_load_dword v116, v[232:233], off
	v_or_b32_e32 v232, 7, v94
	v_mad_i64_i32 v[232:233], s[2:3], v232, s23, v[56:57]
	global_load_dword v118, v[232:233], off
	v_or_b32_e32 v232, 8, v94
	v_mad_i64_i32 v[232:233], s[2:3], v232, s23, v[56:57]
	global_load_dword v120, v[232:233], off
	v_or_b32_e32 v232, 9, v94
	v_mad_i64_i32 v[232:233], s[2:3], v232, s23, v[56:57]
	global_load_dword v122, v[232:233], off
	v_or_b32_e32 v232, 10, v94
	v_mad_i64_i32 v[232:233], s[2:3], v232, s23, v[56:57]
	global_load_dword v124, v[232:233], off
	v_or_b32_e32 v232, 11, v94
	v_mad_i64_i32 v[232:233], s[2:3], v232, s23, v[56:57]
	global_load_dword v126, v[232:233], off
	v_or_b32_e32 v232, 12, v94
	v_mad_i64_i32 v[232:233], s[2:3], v232, s23, v[56:57]
	global_load_dword v128, v[232:233], off
	v_or_b32_e32 v232, 13, v94
	v_mad_i64_i32 v[232:233], s[2:3], v232, s23, v[56:57]
	global_load_dword v130, v[232:233], off
	v_or_b32_e32 v232, 14, v94
	v_mad_i64_i32 v[232:233], s[2:3], v232, s23, v[56:57]
	global_load_dword v132, v[232:233], off
	v_or_b32_e32 v232, 15, v94
	v_mad_i64_i32 v[232:233], s[2:3], v232, s23, v[56:57]
	global_load_dword v134, v[232:233], off
	v_or_b32_e32 v232, 16, v94
	v_mad_i64_i32 v[232:233], s[2:3], v232, s23, v[56:57]
	global_load_dword v136, v[232:233], off
	v_or_b32_e32 v232, 17, v94
	v_mad_i64_i32 v[232:233], s[2:3], v232, s23, v[56:57]
	global_load_dword v138, v[232:233], off
	v_or_b32_e32 v232, 18, v94
	v_mad_i64_i32 v[232:233], s[2:3], v232, s23, v[56:57]
	global_load_dword v140, v[232:233], off
	v_or_b32_e32 v232, 19, v94
	v_mad_i64_i32 v[232:233], s[2:3], v232, s23, v[56:57]
	global_load_dword v142, v[232:233], off
	v_or_b32_e32 v232, 20, v94
	v_mad_i64_i32 v[232:233], s[2:3], v232, s23, v[56:57]
	global_load_dword v144, v[232:233], off
	v_or_b32_e32 v232, 21, v94
	v_mad_i64_i32 v[232:233], s[2:3], v232, s23, v[56:57]
	global_load_dword v146, v[232:233], off
	v_or_b32_e32 v232, 22, v94
	v_mad_i64_i32 v[232:233], s[2:3], v232, s23, v[56:57]
	global_load_dword v148, v[232:233], off
	v_or_b32_e32 v232, 23, v94
	v_mad_i64_i32 v[232:233], s[2:3], v232, s23, v[56:57]
	global_load_dword v150, v[232:233], off
	v_or_b32_e32 v232, 24, v94
	v_mad_i64_i32 v[232:233], s[2:3], v232, s23, v[56:57]
	global_load_dword v152, v[232:233], off
	v_or_b32_e32 v232, 25, v94
	v_mad_i64_i32 v[232:233], s[2:3], v232, s23, v[56:57]
	global_load_dword v154, v[232:233], off
	v_or_b32_e32 v232, 26, v94
	v_mad_i64_i32 v[232:233], s[2:3], v232, s23, v[56:57]
	global_load_dword v156, v[232:233], off
	v_or_b32_e32 v232, 27, v94
	v_mad_i64_i32 v[232:233], s[2:3], v232, s23, v[56:57]
	global_load_dword v158, v[232:233], off
	v_or_b32_e32 v232, 28, v94
	v_mad_i64_i32 v[232:233], s[2:3], v232, s23, v[56:57]
	global_load_dword v160, v[232:233], off
	v_or_b32_e32 v232, 29, v94
	v_mad_i64_i32 v[232:233], s[2:3], v232, s23, v[56:57]
	global_load_dword v162, v[232:233], off
	v_or_b32_e32 v232, 30, v94
	v_mad_i64_i32 v[232:233], s[2:3], v232, s23, v[56:57]
	global_load_dword v164, v[232:233], off
	v_or_b32_e32 v232, 31, v94
	v_mad_i64_i32 v[232:233], s[2:3], v232, s23, v[56:57]
	global_load_dword v166, v[232:233], off
	v_lshl_add_u32 v95, v94, 2, 0
	ds_read_b128 v[10:13], v95
	ds_read_b128 v[14:17], v95 offset:16
	ds_read_b128 v[18:21], v95 offset:16384
	ds_read_b128 v[34:37], v95 offset:20480
	ds_read_b128 v[38:41], v95 offset:4096
	ds_read_b128 v[2:5], v95 offset:4112
	ds_read_b128 v[26:29], v95 offset:8192
	ds_read_b128 v[22:25], v95 offset:8208
	ds_read_b128 v[42:45], v95 offset:12288
	ds_read_b128 v[6:9], v95 offset:12304
	s_waitcnt lgkmcnt(9)
	v_mov_b32_e32 v82, v10
	s_waitcnt lgkmcnt(5)
	v_mov_b32_e32 v83, v38
	s_waitcnt lgkmcnt(3)
	v_mov_b32_e32 v64, v26
	s_waitcnt lgkmcnt(1)
	v_mov_b32_e32 v65, v42
	v_mov_b32_e32 v38, v11
	v_mov_b32_e32 v42, v27
	v_mov_b32_e32 v70, v12
	v_mov_b32_e32 v71, v40
	v_mov_b32_e32 v40, v13
	v_mov_b32_e32 v68, v28
	v_mov_b32_e32 v69, v44
	v_mov_b32_e32 v44, v29
	ds_read_b128 v[26:29], v95 offset:16400
	ds_read_b128 v[10:13], v95 offset:20496
	v_mov_b32_e32 v72, v18
	v_mov_b32_e32 v73, v34
	v_mov_b32_e32 v34, v19
	v_mov_b32_e32 v74, v20
	v_mov_b32_e32 v75, v36
	v_mov_b32_e32 v36, v21
	ds_read_b128 v[78:81], v95 offset:24576
	ds_read_b128 v[30:33], v95 offset:24592
	ds_read_b128 v[46:49], v95 offset:28672
	ds_read_b128 v[18:21], v95 offset:28688
	v_cmp_eq_u32_e64 s[4:5], v94, v91
	s_or_b64 s[26:27], s[4:5], s[26:27]
	s_waitcnt lgkmcnt(3)
	v_mov_b32_e32 v76, v78
	s_waitcnt lgkmcnt(1)
	v_mov_b32_e32 v77, v46
	v_mov_b32_e32 v46, v79
	v_mov_b32_e32 v78, v80
	v_mov_b32_e32 v79, v48
	v_mov_b32_e32 v48, v81
	s_waitcnt vmcnt(31)
	v_pk_fma_f32 v[82:83], v[82:83], v[104:105], v[58:59] op_sel_hi:[1,0,1]
	s_waitcnt vmcnt(30)
	v_pk_fma_f32 v[38:39], v[38:39], v[106:107], v[82:83] op_sel_hi:[1,0,1]
	s_waitcnt vmcnt(29)
	v_pk_fma_f32 v[38:39], v[70:71], v[108:109], v[38:39] op_sel_hi:[1,0,1]
	s_waitcnt vmcnt(28)
	v_pk_fma_f32 v[38:39], v[40:41], v[110:111], v[38:39] op_sel_hi:[1,0,1]
	v_pk_fma_f32 v[40:41], v[64:65], v[104:105], v[66:67] op_sel_hi:[1,0,1]
	s_nop 0
	v_pk_fma_f32 v[40:41], v[42:43], v[106:107], v[40:41] op_sel_hi:[1,0,1]
	v_pk_fma_f32 v[42:43], v[72:73], v[104:105], v[62:63] op_sel_hi:[1,0,1]
	v_pk_fma_f32 v[40:41], v[68:69], v[108:109], v[40:41] op_sel_hi:[1,0,1]
	v_pk_fma_f32 v[34:35], v[34:35], v[106:107], v[42:43] op_sel_hi:[1,0,1]
	v_pk_fma_f32 v[40:41], v[44:45], v[110:111], v[40:41] op_sel_hi:[1,0,1]
	v_pk_fma_f32 v[34:35], v[74:75], v[108:109], v[34:35] op_sel_hi:[1,0,1]
	v_mov_b32_e32 v62, v32
	v_pk_fma_f32 v[42:43], v[36:37], v[110:111], v[34:35] op_sel_hi:[1,0,1]
	v_pk_fma_f32 v[34:35], v[76:77], v[104:105], v[60:61] op_sel_hi:[1,0,1]
	v_mov_b32_e32 v60, v16
	v_pk_fma_f32 v[34:35], v[46:47], v[106:107], v[34:35] op_sel_hi:[1,0,1]
	v_mov_b32_e32 v61, v4
	v_pk_fma_f32 v[34:35], v[78:79], v[108:109], v[34:35] op_sel_hi:[1,0,1]
	v_mov_b32_e32 v4, v17
	v_pk_fma_f32 v[48:49], v[48:49], v[110:111], v[34:35] op_sel_hi:[1,0,1]
	ds_read_b128 v[34:37], v95 offset:32768
	ds_read_b128 v[44:47], v95 offset:32784
	v_mov_b32_e32 v16, v26
	v_mov_b32_e32 v17, v10
	v_mov_b32_e32 v10, v27
	s_waitcnt lgkmcnt(1)
	v_fmac_f32_e32 v93, v34, v104
	v_fmac_f32_e32 v93, v35, v106
	v_fmac_f32_e32 v93, v36, v108
	v_fmac_f32_e32 v93, v37, v110
	v_mov_b32_e32 v34, v14
	v_mov_b32_e32 v35, v2
	v_mov_b32_e32 v2, v15
	v_mov_b32_e32 v14, v22
	v_mov_b32_e32 v15, v6
	v_mov_b32_e32 v36, v30
	v_mov_b32_e32 v37, v18
	v_mov_b32_e32 v6, v23
	v_mov_b32_e32 v18, v31
	v_mov_b32_e32 v63, v20
	v_mov_b32_e32 v20, v33
	s_waitcnt vmcnt(27)
	v_pk_fma_f32 v[30:31], v[34:35], v[112:113], v[38:39] op_sel_hi:[1,0,1]
	v_pk_fma_f32 v[32:33], v[14:15], v[112:113], v[40:41] op_sel_hi:[1,0,1]
	v_pk_fma_f32 v[34:35], v[16:17], v[112:113], v[42:43] op_sel_hi:[1,0,1]
	v_pk_fma_f32 v[36:37], v[36:37], v[112:113], v[48:49] op_sel_hi:[1,0,1]
	v_mov_b32_e32 v22, v24
	v_mov_b32_e32 v23, v8
	v_mov_b32_e32 v8, v25
	v_mov_b32_e32 v24, v28
	v_mov_b32_e32 v25, v12
	v_mov_b32_e32 v12, v29
	ds_read_b128 v[26:29], v95 offset:32
	ds_read_b128 v[14:17], v95 offset:48
	s_waitcnt vmcnt(26)
	v_pk_fma_f32 v[2:3], v[2:3], v[114:115], v[30:31] op_sel_hi:[1,0,1]
	v_pk_fma_f32 v[6:7], v[6:7], v[114:115], v[32:33] op_sel_hi:[1,0,1]
	v_pk_fma_f32 v[10:11], v[10:11], v[114:115], v[34:35] op_sel_hi:[1,0,1]
	v_pk_fma_f32 v[18:19], v[18:19], v[114:115], v[36:37] op_sel_hi:[1,0,1]
	ds_read_b128 v[34:37], v95 offset:4128
	ds_read_b128 v[30:33], v95 offset:8224
	ds_read_b128 v[38:41], v95 offset:12320
	s_waitcnt lgkmcnt(5)
	v_fmac_f32_e32 v93, v44, v112
	v_fmac_f32_e32 v93, v45, v114
	s_waitcnt vmcnt(25)
	v_pk_fma_f32 v[2:3], v[60:61], v[116:117], v[2:3] op_sel_hi:[1,0,1]
	v_pk_fma_f32 v[6:7], v[22:23], v[116:117], v[6:7] op_sel_hi:[1,0,1]
	v_pk_fma_f32 v[10:11], v[24:25], v[116:117], v[10:11] op_sel_hi:[1,0,1]
	v_pk_fma_f32 v[18:19], v[62:63], v[116:117], v[18:19] op_sel_hi:[1,0,1]
	ds_read_b128 v[76:79], v95 offset:16416
	ds_read_b128 v[42:45], v95 offset:20512
	v_fmac_f32_e32 v93, v46, v116
	s_waitcnt vmcnt(24)
	v_pk_fma_f32 v[60:61], v[4:5], v[118:119], v[2:3] op_sel_hi:[1,0,1]
	v_pk_fma_f32 v[66:67], v[8:9], v[118:119], v[6:7] op_sel_hi:[1,0,1]
	v_pk_fma_f32 v[64:65], v[12:13], v[118:119], v[10:11] op_sel_hi:[1,0,1]
	ds_read_b128 v[2:5], v95 offset:4144
	v_pk_fma_f32 v[62:63], v[20:21], v[118:119], v[18:19] op_sel_hi:[1,0,1]
	ds_read_b128 v[22:25], v95 offset:8240
	v_fmac_f32_e32 v93, v47, v118
	ds_read_b128 v[6:9], v95 offset:12336
	s_waitcnt lgkmcnt(9)
	v_mov_b32_e32 v84, v26
	s_waitcnt lgkmcnt(7)
	v_mov_b32_e32 v85, v34
	v_mov_b32_e32 v34, v27
	v_mov_b32_e32 v68, v28
	v_mov_b32_e32 v69, v36
	v_mov_b32_e32 v36, v29
	s_waitcnt lgkmcnt(6)
	v_mov_b32_e32 v70, v30
	s_waitcnt lgkmcnt(5)
	v_mov_b32_e32 v71, v38
	v_mov_b32_e32 v38, v31
	v_mov_b32_e32 v72, v32
	v_mov_b32_e32 v73, v40
	v_mov_b32_e32 v40, v33
	ds_read_b128 v[26:29], v95 offset:16432
	ds_read_b128 v[10:13], v95 offset:20528
	ds_read_b128 v[80:83], v95 offset:24608
	ds_read_b128 v[30:33], v95 offset:24624
	ds_read_b128 v[46:49], v95 offset:28704
	ds_read_b128 v[18:21], v95 offset:28720
	s_waitcnt lgkmcnt(10)
	v_mov_b32_e32 v74, v76
	s_waitcnt lgkmcnt(9)
	v_mov_b32_e32 v75, v42
	v_mov_b32_e32 v42, v77
	v_mov_b32_e32 v76, v78
	v_mov_b32_e32 v77, v44
	v_mov_b32_e32 v44, v79
	s_waitcnt lgkmcnt(3)
	v_mov_b32_e32 v78, v80
	s_waitcnt lgkmcnt(1)
	v_mov_b32_e32 v79, v46
	v_mov_b32_e32 v46, v81
	v_mov_b32_e32 v80, v82
	v_mov_b32_e32 v81, v48
	v_mov_b32_e32 v48, v83
	s_waitcnt vmcnt(23)
	v_pk_fma_f32 v[82:83], v[84:85], v[120:121], v[60:61] op_sel_hi:[1,0,1]
	s_waitcnt vmcnt(22)
	v_pk_fma_f32 v[34:35], v[34:35], v[122:123], v[82:83] op_sel_hi:[1,0,1]
	s_waitcnt vmcnt(21)
	v_pk_fma_f32 v[34:35], v[68:69], v[124:125], v[34:35] op_sel_hi:[1,0,1]
	s_waitcnt vmcnt(20)
	v_pk_fma_f32 v[68:69], v[36:37], v[126:127], v[34:35] op_sel_hi:[1,0,1]
	v_pk_fma_f32 v[34:35], v[70:71], v[120:121], v[66:67] op_sel_hi:[1,0,1]
	s_nop 0
	v_pk_fma_f32 v[34:35], v[38:39], v[122:123], v[34:35] op_sel_hi:[1,0,1]
	s_nop 0
	v_pk_fma_f32 v[34:35], v[72:73], v[124:125], v[34:35] op_sel_hi:[1,0,1]
	s_nop 0
	v_pk_fma_f32 v[38:39], v[40:41], v[126:127], v[34:35] op_sel_hi:[1,0,1]
	v_pk_fma_f32 v[34:35], v[74:75], v[120:121], v[64:65] op_sel_hi:[1,0,1]
	s_nop 0
	v_pk_fma_f32 v[34:35], v[42:43], v[122:123], v[34:35] op_sel_hi:[1,0,1]
	s_nop 0
	v_pk_fma_f32 v[34:35], v[76:77], v[124:125], v[34:35] op_sel_hi:[1,0,1]
	s_nop 0
	v_pk_fma_f32 v[40:41], v[44:45], v[126:127], v[34:35] op_sel_hi:[1,0,1]
	v_pk_fma_f32 v[34:35], v[78:79], v[120:121], v[62:63] op_sel_hi:[1,0,1]
	s_waitcnt lgkmcnt(0)
	v_mov_b32_e32 v59, v20
	v_pk_fma_f32 v[34:35], v[46:47], v[122:123], v[34:35] op_sel_hi:[1,0,1]
	v_mov_b32_e32 v20, v33
	v_pk_fma_f32 v[34:35], v[80:81], v[124:125], v[34:35] op_sel_hi:[1,0,1]
	s_nop 0
	v_pk_fma_f32 v[42:43], v[48:49], v[126:127], v[34:35] op_sel_hi:[1,0,1]
	ds_read_b128 v[34:37], v95 offset:32800
	ds_read_b128 v[44:47], v95 offset:32816
	v_mov_b32_e32 v48, v28
	v_mov_b32_e32 v49, v12
	v_mov_b32_e32 v12, v29
	s_waitcnt lgkmcnt(1)
	v_fmac_f32_e32 v93, v34, v120
	v_fmac_f32_e32 v93, v35, v122
	v_fmac_f32_e32 v93, v36, v124
	v_mov_b32_e32 v34, v14
	v_mov_b32_e32 v35, v2
	v_fmac_f32_e32 v93, v37, v126
	v_mov_b32_e32 v2, v15
	v_mov_b32_e32 v14, v22
	v_mov_b32_e32 v15, v6
	v_mov_b32_e32 v6, v23
	v_mov_b32_e32 v22, v24
	v_mov_b32_e32 v23, v8
	v_mov_b32_e32 v8, v25
	v_mov_b32_e32 v24, v26
	v_mov_b32_e32 v25, v10
	v_mov_b32_e32 v10, v27
	v_mov_b32_e32 v26, v30
	v_mov_b32_e32 v27, v18
	v_mov_b32_e32 v18, v31
	s_waitcnt vmcnt(19)
	v_pk_fma_f32 v[30:31], v[34:35], v[128:129], v[68:69] op_sel_hi:[1,0,1]
	v_mov_b32_e32 v36, v16
	v_mov_b32_e32 v37, v4
	v_mov_b32_e32 v58, v32
	v_pk_fma_f32 v[32:33], v[14:15], v[128:129], v[38:39] op_sel_hi:[1,0,1]
	v_pk_fma_f32 v[34:35], v[26:27], v[128:129], v[42:43] op_sel_hi:[1,0,1]
	s_waitcnt lgkmcnt(0)
	v_fmac_f32_e32 v93, v44, v128
	s_waitcnt vmcnt(18)
	v_pk_fma_f32 v[2:3], v[2:3], v[130:131], v[30:31] op_sel_hi:[1,0,1]
	v_mov_b32_e32 v4, v17
	ds_read_b128 v[14:17], v95 offset:64
	v_pk_fma_f32 v[24:25], v[24:25], v[128:129], v[40:41] op_sel_hi:[1,0,1]
	ds_read_b128 v[26:29], v95 offset:4160
	v_pk_fma_f32 v[6:7], v[6:7], v[130:131], v[32:33] op_sel_hi:[1,0,1]
	v_pk_fma_f32 v[18:19], v[18:19], v[130:131], v[34:35] op_sel_hi:[1,0,1]
	v_fmac_f32_e32 v93, v45, v130
	ds_read_b128 v[30:33], v95 offset:8256
	s_waitcnt vmcnt(17)
	v_pk_fma_f32 v[2:3], v[36:37], v[132:133], v[2:3] op_sel_hi:[1,0,1]
	ds_read_b128 v[38:41], v95 offset:12352
	ds_read_b128 v[34:37], v95 offset:16448
	ds_read_b128 v[42:45], v95 offset:20544
	v_pk_fma_f32 v[10:11], v[10:11], v[130:131], v[24:25] op_sel_hi:[1,0,1]
	v_pk_fma_f32 v[6:7], v[22:23], v[132:133], v[6:7] op_sel_hi:[1,0,1]
	v_pk_fma_f32 v[10:11], v[48:49], v[132:133], v[10:11] op_sel_hi:[1,0,1]
	v_pk_fma_f32 v[18:19], v[58:59], v[132:133], v[18:19] op_sel_hi:[1,0,1]
	v_fmac_f32_e32 v93, v46, v132
	s_waitcnt vmcnt(16)
	v_pk_fma_f32 v[68:69], v[4:5], v[134:135], v[2:3] op_sel_hi:[1,0,1]
	v_pk_fma_f32 v[64:65], v[8:9], v[134:135], v[6:7] op_sel_hi:[1,0,1]
	ds_read_b128 v[22:25], v95 offset:80
	v_pk_fma_f32 v[62:63], v[12:13], v[134:135], v[10:11] op_sel_hi:[1,0,1]
	ds_read_b128 v[2:5], v95 offset:4176
	v_pk_fma_f32 v[58:59], v[20:21], v[134:135], v[18:19] op_sel_hi:[1,0,1]
	ds_read_b128 v[18:21], v95 offset:8272
	v_fmac_f32_e32 v93, v47, v134
	ds_read_b128 v[6:9], v95 offset:12368
	s_waitcnt lgkmcnt(9)
	v_mov_b32_e32 v84, v14
	s_waitcnt lgkmcnt(8)
	v_mov_b32_e32 v85, v26
	v_mov_b32_e32 v26, v15
	v_mov_b32_e32 v66, v16
	v_mov_b32_e32 v67, v28
	v_mov_b32_e32 v28, v17
	s_waitcnt lgkmcnt(7)
	v_mov_b32_e32 v70, v30
	s_waitcnt lgkmcnt(6)
	v_mov_b32_e32 v71, v38
	v_mov_b32_e32 v38, v31
	v_mov_b32_e32 v72, v32
	v_mov_b32_e32 v73, v40
	v_mov_b32_e32 v40, v33
	ds_read_b128 v[30:33], v95 offset:16464
	s_waitcnt lgkmcnt(6)
	v_mov_b32_e32 v74, v34
	ds_read_b128 v[10:13], v95 offset:20560
	s_waitcnt lgkmcnt(6)
	v_mov_b32_e32 v75, v42
	v_mov_b32_e32 v42, v35
	v_mov_b32_e32 v76, v36
	v_mov_b32_e32 v77, v44
	v_mov_b32_e32 v44, v37
	ds_read_b128 v[80:83], v95 offset:24640
	ds_read_b128 v[34:37], v95 offset:24656
	ds_read_b128 v[46:49], v95 offset:28736
	ds_read_b128 v[14:17], v95 offset:28752
	s_waitcnt lgkmcnt(3)
	v_mov_b32_e32 v78, v80
	s_waitcnt lgkmcnt(1)
	v_mov_b32_e32 v79, v46
	v_mov_b32_e32 v46, v81
	v_mov_b32_e32 v80, v82
	v_mov_b32_e32 v81, v48
	v_mov_b32_e32 v48, v83
	s_waitcnt vmcnt(15)
	v_pk_fma_f32 v[82:83], v[84:85], v[136:137], v[68:69] op_sel_hi:[1,0,1]
	s_waitcnt vmcnt(14)
	v_pk_fma_f32 v[26:27], v[26:27], v[138:139], v[82:83] op_sel_hi:[1,0,1]
	s_waitcnt vmcnt(13)
	v_pk_fma_f32 v[26:27], v[66:67], v[140:141], v[26:27] op_sel_hi:[1,0,1]
	s_waitcnt vmcnt(12)
	v_pk_fma_f32 v[66:67], v[28:29], v[142:143], v[26:27] op_sel_hi:[1,0,1]
	v_pk_fma_f32 v[26:27], v[70:71], v[136:137], v[64:65] op_sel_hi:[1,0,1]
	s_nop 0
	v_pk_fma_f32 v[26:27], v[38:39], v[138:139], v[26:27] op_sel_hi:[1,0,1]
	s_nop 0
	v_pk_fma_f32 v[26:27], v[72:73], v[140:141], v[26:27] op_sel_hi:[1,0,1]
	s_nop 0
	v_pk_fma_f32 v[38:39], v[40:41], v[142:143], v[26:27] op_sel_hi:[1,0,1]
	v_pk_fma_f32 v[26:27], v[74:75], v[136:137], v[62:63] op_sel_hi:[1,0,1]
	s_nop 0
	v_pk_fma_f32 v[26:27], v[42:43], v[138:139], v[26:27] op_sel_hi:[1,0,1]
	s_nop 0
	v_pk_fma_f32 v[26:27], v[76:77], v[140:141], v[26:27] op_sel_hi:[1,0,1]
	s_nop 0
	v_pk_fma_f32 v[40:41], v[44:45], v[142:143], v[26:27] op_sel_hi:[1,0,1]
	v_pk_fma_f32 v[26:27], v[78:79], v[136:137], v[58:59] op_sel_hi:[1,0,1]
	v_mov_b32_e32 v58, v36
	v_pk_fma_f32 v[26:27], v[46:47], v[138:139], v[26:27] op_sel_hi:[1,0,1]
	s_waitcnt lgkmcnt(0)
	v_mov_b32_e32 v59, v16
	v_pk_fma_f32 v[26:27], v[80:81], v[140:141], v[26:27] op_sel_hi:[1,0,1]
	v_mov_b32_e32 v16, v37
	v_pk_fma_f32 v[42:43], v[48:49], v[142:143], v[26:27] op_sel_hi:[1,0,1]
	ds_read_b128 v[26:29], v95 offset:32832
	ds_read_b128 v[44:47], v95 offset:32848
	v_mov_b32_e32 v48, v32
	v_mov_b32_e32 v49, v12
	v_mov_b32_e32 v12, v33
	s_waitcnt lgkmcnt(1)
	v_fmac_f32_e32 v93, v26, v136
	v_fmac_f32_e32 v93, v27, v138
	v_fmac_f32_e32 v93, v28, v140
	v_fmac_f32_e32 v93, v29, v142
	v_mov_b32_e32 v28, v20
	v_mov_b32_e32 v29, v8
	v_mov_b32_e32 v8, v21
	v_mov_b32_e32 v20, v34
	v_mov_b32_e32 v21, v14
	v_mov_b32_e32 v26, v22
	v_mov_b32_e32 v27, v2
	v_mov_b32_e32 v2, v23
	v_mov_b32_e32 v22, v24
	v_mov_b32_e32 v23, v4
	v_mov_b32_e32 v4, v25
	v_mov_b32_e32 v24, v18
	v_mov_b32_e32 v25, v6
	v_mov_b32_e32 v6, v19
	v_mov_b32_e32 v18, v30
	v_mov_b32_e32 v19, v10
	v_mov_b32_e32 v14, v35
	s_waitcnt vmcnt(11)
	v_pk_fma_f32 v[36:37], v[20:21], v[144:145], v[42:43] op_sel_hi:[1,0,1]
	v_mov_b32_e32 v10, v31
	v_pk_fma_f32 v[34:35], v[18:19], v[144:145], v[40:41] op_sel_hi:[1,0,1]
	s_waitcnt lgkmcnt(0)
	v_fmac_f32_e32 v93, v44, v144
	s_waitcnt vmcnt(10)
	v_pk_fma_f32 v[14:15], v[14:15], v[146:147], v[36:37] op_sel_hi:[1,0,1]
	v_pk_fma_f32 v[24:25], v[24:25], v[144:145], v[38:39] op_sel_hi:[1,0,1]
	ds_read_b128 v[30:33], v95 offset:96
	ds_read_b128 v[18:21], v95 offset:4192
	v_pk_fma_f32 v[10:11], v[10:11], v[146:147], v[34:35] op_sel_hi:[1,0,1]
	v_fmac_f32_e32 v93, v45, v146
	ds_read_b128 v[34:37], v95 offset:8288
	ds_read_b128 v[38:41], v95 offset:12384
	s_waitcnt vmcnt(9)
	v_pk_fma_f32 v[14:15], v[58:59], v[148:149], v[14:15] op_sel_hi:[1,0,1]
	ds_read_b128 v[58:61], v95 offset:16480
	ds_read_b128 v[42:45], v95 offset:20576
	v_pk_fma_f32 v[26:27], v[26:27], v[144:145], v[66:67] op_sel_hi:[1,0,1]
	v_pk_fma_f32 v[6:7], v[6:7], v[146:147], v[24:25] op_sel_hi:[1,0,1]
	v_pk_fma_f32 v[2:3], v[2:3], v[146:147], v[26:27] op_sel_hi:[1,0,1]
	v_pk_fma_f32 v[6:7], v[28:29], v[148:149], v[6:7] op_sel_hi:[1,0,1]
	v_pk_fma_f32 v[2:3], v[22:23], v[148:149], v[2:3] op_sel_hi:[1,0,1]
	v_pk_fma_f32 v[10:11], v[48:49], v[148:149], v[10:11] op_sel_hi:[1,0,1]
	s_waitcnt vmcnt(8)
	v_pk_fma_f32 v[62:63], v[4:5], v[150:151], v[2:3] op_sel_hi:[1,0,1]
	v_pk_fma_f32 v[74:75], v[8:9], v[150:151], v[6:7] op_sel_hi:[1,0,1]
	ds_read_b128 v[26:29], v95 offset:112
	v_pk_fma_f32 v[72:73], v[12:13], v[150:151], v[10:11] op_sel_hi:[1,0,1]
	ds_read_b128 v[2:5], v95 offset:4208
	ds_read_b128 v[22:25], v95 offset:8304
	v_fmac_f32_e32 v93, v46, v148
	ds_read_b128 v[6:9], v95 offset:12400
	s_waitcnt lgkmcnt(9)
	v_mov_b32_e32 v64, v30
	s_waitcnt lgkmcnt(8)
	v_mov_b32_e32 v65, v18
	v_mov_b32_e32 v18, v31
	v_mov_b32_e32 v66, v32
	v_mov_b32_e32 v67, v20
	v_mov_b32_e32 v20, v33
	s_waitcnt lgkmcnt(7)
	v_mov_b32_e32 v76, v34
	s_waitcnt lgkmcnt(6)
	v_mov_b32_e32 v77, v38
	v_mov_b32_e32 v38, v35
	v_mov_b32_e32 v78, v36
	v_mov_b32_e32 v79, v40
	v_mov_b32_e32 v40, v37
	ds_read_b128 v[30:33], v95 offset:16496
	s_waitcnt lgkmcnt(6)
	v_mov_b32_e32 v80, v58
	ds_read_b128 v[10:13], v95 offset:20592
	s_waitcnt lgkmcnt(6)
	v_mov_b32_e32 v81, v42
	v_mov_b32_e32 v42, v59
	v_mov_b32_e32 v82, v60
	v_mov_b32_e32 v83, v44
	v_mov_b32_e32 v44, v61
	ds_read_b128 v[58:61], v95 offset:24672
	ds_read_b128 v[34:37], v95 offset:24688
	v_pk_fma_f32 v[70:71], v[16:17], v[150:151], v[14:15] op_sel_hi:[1,0,1]
	v_fmac_f32_e32 v93, v47, v150
	ds_read_b128 v[46:49], v95 offset:28768
	ds_read_b128 v[14:17], v95 offset:28784
	s_waitcnt lgkmcnt(3)
	v_mov_b32_e32 v84, v58
	v_mov_b32_e32 v86, v60
	s_waitcnt lgkmcnt(1)
	v_mov_b32_e32 v85, v46
	v_mov_b32_e32 v46, v59
	v_mov_b32_e32 v87, v48
	v_mov_b32_e32 v48, v61
	s_waitcnt vmcnt(7)
	v_pk_fma_f32 v[88:89], v[64:65], v[152:153], v[62:63] op_sel_hi:[1,0,1]
	s_waitcnt vmcnt(6)
	v_pk_fma_f32 v[18:19], v[18:19], v[154:155], v[88:89] op_sel_hi:[1,0,1]
	s_waitcnt vmcnt(5)
	v_pk_fma_f32 v[18:19], v[66:67], v[156:157], v[18:19] op_sel_hi:[1,0,1]
	s_waitcnt vmcnt(4)
	v_pk_fma_f32 v[66:67], v[20:21], v[158:159], v[18:19] op_sel_hi:[1,0,1]
	v_pk_fma_f32 v[18:19], v[76:77], v[152:153], v[74:75] op_sel_hi:[1,0,1]
	s_nop 0
	v_pk_fma_f32 v[18:19], v[38:39], v[154:155], v[18:19] op_sel_hi:[1,0,1]
	s_nop 0
	v_pk_fma_f32 v[18:19], v[78:79], v[156:157], v[18:19] op_sel_hi:[1,0,1]
	s_nop 0
	v_pk_fma_f32 v[38:39], v[40:41], v[158:159], v[18:19] op_sel_hi:[1,0,1]
	v_pk_fma_f32 v[18:19], v[80:81], v[152:153], v[72:73] op_sel_hi:[1,0,1]
	s_nop 0
	v_pk_fma_f32 v[18:19], v[42:43], v[154:155], v[18:19] op_sel_hi:[1,0,1]
	s_nop 0
	v_pk_fma_f32 v[18:19], v[82:83], v[156:157], v[18:19] op_sel_hi:[1,0,1]
	s_nop 0
	v_pk_fma_f32 v[40:41], v[44:45], v[158:159], v[18:19] op_sel_hi:[1,0,1]
	v_pk_fma_f32 v[18:19], v[84:85], v[152:153], v[70:71] op_sel_hi:[1,0,1]
	s_nop 0
	v_pk_fma_f32 v[18:19], v[46:47], v[154:155], v[18:19] op_sel_hi:[1,0,1]
	s_nop 0
	v_pk_fma_f32 v[18:19], v[86:87], v[156:157], v[18:19] op_sel_hi:[1,0,1]
	s_nop 0
	v_pk_fma_f32 v[42:43], v[48:49], v[158:159], v[18:19] op_sel_hi:[1,0,1]
	ds_read_b128 v[44:47], v95 offset:32864
	ds_read_b128 v[18:21], v95 offset:32880
	s_waitcnt lgkmcnt(1)
	v_fmac_f32_e32 v93, v44, v152
	v_fmac_f32_e32 v93, v45, v154
	v_fmac_f32_e32 v93, v46, v156
	v_fmac_f32_e32 v93, v47, v158
	v_mov_b32_e32 v44, v26
	v_mov_b32_e32 v45, v2
	v_mov_b32_e32 v2, v27
	v_mov_b32_e32 v26, v28
	v_mov_b32_e32 v27, v4
	v_mov_b32_e32 v4, v29
	v_mov_b32_e32 v28, v22
	v_mov_b32_e32 v29, v6
	v_mov_b32_e32 v6, v23
	v_mov_b32_e32 v22, v24
	v_mov_b32_e32 v23, v8
	v_mov_b32_e32 v8, v25
	v_mov_b32_e32 v46, v30
	v_mov_b32_e32 v47, v10
	v_mov_b32_e32 v24, v32
	v_mov_b32_e32 v25, v12
	v_mov_b32_e32 v12, v33
	v_mov_b32_e32 v32, v34
	v_mov_b32_e32 v33, v14
	v_add_u32_e32 v34, 32, v94
	v_mov_b32_e32 v10, v31
	v_mov_b32_e32 v14, v35
	v_mov_b32_e32 v30, v36
	v_mov_b32_e32 v31, v16
	v_mov_b32_e32 v16, v37
	v_mov_b32_e32 v94, v34
	s_waitcnt vmcnt(3)
	v_pk_fma_f32 v[34:35], v[44:45], v[160:161], v[66:67] op_sel_hi:[1,0,1]
	v_pk_fma_f32 v[28:29], v[28:29], v[160:161], v[38:39] op_sel_hi:[1,0,1]
	v_pk_fma_f32 v[36:37], v[46:47], v[160:161], v[40:41] op_sel_hi:[1,0,1]
	v_pk_fma_f32 v[32:33], v[32:33], v[160:161], v[42:43] op_sel_hi:[1,0,1]
	s_waitcnt lgkmcnt(0)
	v_fmac_f32_e32 v93, v18, v160
	s_waitcnt vmcnt(2)
	v_pk_fma_f32 v[2:3], v[2:3], v[162:163], v[34:35] op_sel_hi:[1,0,1]
	v_pk_fma_f32 v[6:7], v[6:7], v[162:163], v[28:29] op_sel_hi:[1,0,1]
	v_pk_fma_f32 v[10:11], v[10:11], v[162:163], v[36:37] op_sel_hi:[1,0,1]
	v_pk_fma_f32 v[14:15], v[14:15], v[162:163], v[32:33] op_sel_hi:[1,0,1]
	v_fmac_f32_e32 v93, v19, v162
	s_waitcnt vmcnt(1)
	v_pk_fma_f32 v[2:3], v[26:27], v[164:165], v[2:3] op_sel_hi:[1,0,1]
	v_pk_fma_f32 v[6:7], v[22:23], v[164:165], v[6:7] op_sel_hi:[1,0,1]
	v_pk_fma_f32 v[10:11], v[24:25], v[164:165], v[10:11] op_sel_hi:[1,0,1]
	v_pk_fma_f32 v[14:15], v[30:31], v[164:165], v[14:15] op_sel_hi:[1,0,1]
	v_fmac_f32_e32 v93, v20, v164
	s_waitcnt vmcnt(0)
	v_pk_fma_f32 v[58:59], v[4:5], v[166:167], v[2:3] op_sel_hi:[1,0,1]
	v_pk_fma_f32 v[66:67], v[8:9], v[166:167], v[6:7] op_sel_hi:[1,0,1]
	v_pk_fma_f32 v[62:63], v[12:13], v[166:167], v[10:11] op_sel_hi:[1,0,1]
	v_pk_fma_f32 v[60:61], v[16:17], v[166:167], v[14:15] op_sel_hi:[1,0,1]
	v_fmac_f32_e32 v93, v21, v166
	s_andn2_b64 exec, exec, s[26:27]
	s_cbranch_execnz .LBB0_17
	s_or_b64 exec, exec, s[26:27]
	ds_write2st64_b32 v92, v58, v59 offset0:144 offset1:145
	ds_write2st64_b32 v92, v66, v67 offset0:146 offset1:147
	ds_write2st64_b32 v92, v62, v63 offset0:148 offset1:149
	ds_write2st64_b32 v92, v60, v61 offset0:150 offset1:151
	ds_write_b32 v92, v93 offset:38912
	s_waitcnt lgkmcnt(0)
	s_barrier
	s_and_saveexec_b64 s[2:3], vcc
	s_cbranch_execz .LBB0_15
	s_mul_i32 s4, s28, 0x1800
	s_add_i32 s4, s4, s6
	v_or_b32_e32 v2, s4, v50
	v_ashrrev_i32_e32 v3, 31, v2
	s_mul_hi_i32 s27, s28, 9
	s_mul_i32 s26, s28, 9
	v_lshl_add_u64 v[2:3], v[2:3], 2, s[10:11]
	v_lshl_add_u64 v[4:5], s[6:7], 2, v[54:55]
	s_mov_b64 s[6:7], 0
	v_mov_b32_e32 v6, v1
